# mLSTM item: setup loads issued together with counted waits; gate scan lane-63 broadcasts by v_readlane instead of ds_bpermute
# baseline (speedup 1.0000x reference)
.LBB0_659:
	s_or_b64 exec, exec, s[4:5]
	s_movk_i32 s4, 0x80
	v_cmp_gt_i32_e64 s[6:7], s4, v14
	v_lshl_add_u32 v15, v14, 2, 0
	s_and_saveexec_b64 s[4:5], s[6:7]
	v_add_u32_e32 v0, 0x10c00, v15
	ds_write_b32 v0, v89
	s_or_b64 exec, exec, s[4:5]
	s_lshr_b32 s4, s56, 3
	s_bfe_u32 s57, s56, 0x20001
	s_lshl_b32 s70, s4, 2
	s_or_b32 s68, s70, s57
	s_mov_b32 s5, s69
	s_lshl_b64 s[8:9], s[68:69], 21
	v_ashrrev_i32_e32 v8, 3, v14
	s_lshl_b64 s[4:5], s[4:5], 22
	v_ashrrev_i32_e32 v9, 31, v8
	s_add_u32 s10, s94, s4
	v_lshlrev_b64 v[0:1], 10, v[8:9]
	s_addc_u32 s11, s95, s5
	v_lshl_add_u64 v[0:1], s[10:11], 0, v[0:1]
	s_lshl_b32 s10, s57, 8
	s_mov_b32 s11, s69
	s_lshl_b32 s71, s56, 7
	v_lshl_add_u64 v[0:1], v[0:1], 0, s[10:11]
	s_and_b32 s10, s71, 0x80
	v_lshl_add_u64 v[0:1], v[0:1], 0, s[10:11]
	s_lshl_b64 s[10:11], s[68:69], 15
	v_lshlrev_b32_e32 v4, 3, v14
	s_add_u32 s8, s90, s8
	v_ashrrev_i32_e32 v5, 31, v4
	v_and_b32_e32 v9, 7, v14
	s_addc_u32 s9, s91, s9
	v_readlane_b32 s0, v255, 15
	v_lshlrev_b32_e32 v88, 4, v9
	v_lshl_add_u64 v[12:13], v[4:5], 1, s[8:9]
	s_add_u32 s8, s0, s10
	v_readlane_b32 s0, v255, 16
	v_lshlrev_b32_e32 v10, 2, v14
	v_lshl_add_u64 v[90:91], v[0:1], 0, v[88:89]
	v_and_b32_e32 v0, 0x7f, v14
	s_addc_u32 s9, s0, s11
	v_ashrrev_i32_e32 v11, 31, v10
	v_lshlrev_b32_e32 v88, 2, v0
	v_lshl_add_u64 v[0:1], v[10:11], 2, s[8:9]
	global_load_dwordx4 v[0:3], v[0:1], off
	v_lshlrev_b32_e32 v34, 4, v14
	v_add_u32_e32 v11, 0, v34
	v_add_u32_e32 v11, 0x11b00, v11
	v_readlane_b32 s0, v255, 13
	v_ashrrev_i32_e32 v32, 4, v14
	s_add_u32 s10, s0, s10
	v_readlane_b32 s0, v255, 14
	s_addc_u32 s11, s0, s11
	v_and_b32_e32 v33, 15, v14
	v_mul_lo_u32 v35, v32, s79
	v_lshl_add_u64 v[6:7], s[10:11], 0, v[88:89]
	v_add_u32_e32 v35, 0, v35
	v_lshlrev_b32_e32 v36, 4, v33
	v_add_u32_e32 v123, v35, v36
	v_add_u32_e32 v180, 0x800, v10
	v_ashrrev_i32_e32 v181, 31, v180
	v_lshl_add_u64 v[180:181], v[180:181], 2, s[8:9]
	global_load_dwordx4 v[184:187], v[180:181], off
	v_add_u32_e32 v182, 0x1000, v10
	v_ashrrev_i32_e32 v183, 31, v182
	v_lshl_add_u64 v[182:183], v[182:183], 2, s[8:9]
	global_load_dwordx4 v[188:191], v[182:183], off
	v_add_u32_e32 v208, 0x1800, v10
	v_ashrrev_i32_e32 v209, 31, v208
	v_lshl_add_u64 v[208:209], v[208:209], 2, s[8:9]
	global_load_dwordx4 v[192:195], v[208:209], off
	s_waitcnt vmcnt(3)
	ds_write_b128 v11, v[0:3]
	s_waitcnt vmcnt(2)
	ds_write_b128 v11, v[184:187] offset:8192
	s_waitcnt vmcnt(1)
	ds_write_b128 v11, v[188:191] offset:16384
	s_waitcnt vmcnt(0)
	ds_write_b128 v11, v[192:195] offset:24576
	s_waitcnt vmcnt(0)
	global_load_dwordx4 v[16:19], v[12:13], off
	v_lshl_add_u64 v[0:1], v[12:13], 0, s[64:65]
	global_load_dwordx4 v[20:23], v[0:1], off
	v_lshl_add_u64 v[0:1], v[12:13], 0, s[88:89]
	global_load_dwordx4 v[24:27], v[0:1], off
	v_lshl_add_u64 v[0:1], v[12:13], 0, s[60:61]
	global_load_dwordx4 v[28:31], v[0:1], off
	global_load_dwordx4 v[0:3], v[90:91], off
	global_load_dword v11, v[6:7], off
	s_nop 0
	s_waitcnt vmcnt(0)
	ds_write_b128 v123, v[16:19]
	v_add_u32_e32 v16, 0x2200, v35
	v_add_u32_e32 v124, v16, v36
	v_lshlrev_b32_e32 v19, 2, v32
	ds_write_b128 v124, v[20:23]
	v_and_b32_e32 v17, -16, v14
	v_and_b32_e32 v19, 12, v19
	v_bfe_u32 v20, v14, 6, 2
	v_bitop3_b32 v19, v19, v33, v20 bitop3:0x36
	v_sub_u32_e32 v16, v16, v17
	v_sub_u32_e32 v18, v35, v17
	v_lshlrev_b32_e32 v19, 4, v19
	v_add_u32_e32 v16, 0xfffffe00, v16
	v_add_u32_e32 v125, v18, v19
	v_add_u32_e32 v126, v16, v19
	v_and_b32_e32 v16, 0xfffffc00, v34
	v_lshlrev_b32_e32 v17, 7, v14
	v_lshlrev_b32_e32 v18, 6, v8
	v_add_u32_e32 v16, 0, v16
	v_and_b32_e32 v17, 0x200, v17
	v_and_b32_e32 v18, 0x1c0, v18
	v_add3_u32 v16, v16, v17, v18
	v_and_b32_e32 v17, 48, v34
	v_add_u32_e32 v127, v16, v17
	ds_write_b128 v125, v[24:27] offset:17408
	ds_write_b128 v126, v[28:31] offset:17408
	ds_write_b128 v127, v[0:3] offset:33792
	s_and_saveexec_b64 s[8:9], s[6:7]
	v_add_u32_e32 v0, 0x11100, v15
	ds_write_b32 v0, v11
	s_mov_b64 s[0:1], s[90:91]
	s_or_b64 exec, exec, s[8:9]
	s_mov_b64 s[8:9], 0x8000
	v_lshl_add_u64 v[2:3], v[12:13], 0, s[8:9]
	global_load_dwordx4 v[32:35], v[2:3], off
	s_mov_b64 s[8:9], 0xa000
	v_lshl_add_u64 v[2:3], v[12:13], 0, s[8:9]
	global_load_dwordx4 v[40:43], v[2:3], off
	s_mov_b64 s[8:9], 0xc000
	v_lshl_add_u64 v[2:3], v[12:13], 0, s[8:9]
	global_load_dwordx4 v[44:47], v[2:3], off
	s_mov_b64 s[8:9], 0xe000
	v_lshl_add_u64 v[2:3], v[12:13], 0, s[8:9]
	global_load_dwordx4 v[48:51], v[2:3], off
	v_lshl_add_u64 v[2:3], v[90:91], 0, s[66:67]
	global_load_dwordx4 v[52:55], v[2:3], off
	s_mov_b64 s[8:9], 0x200
	v_lshl_add_u64 v[2:3], v[6:7], 0, s[8:9]
	global_load_dword v129, v[2:3], off
	v_lshl_add_u64 v[2:3], v[12:13], 0, s[66:67]
	global_load_dwordx4 v[16:19], v[2:3], off
	s_mov_b64 s[8:9], 0x12000
	v_lshl_add_u64 v[2:3], v[12:13], 0, s[8:9]
	global_load_dwordx4 v[20:23], v[2:3], off
	s_mov_b64 s[8:9], 0x14000
	v_lshl_add_u64 v[2:3], v[12:13], 0, s[8:9]
	global_load_dwordx4 v[24:27], v[2:3], off
	s_mov_b64 s[8:9], 0x16000
	v_lshl_add_u64 v[2:3], v[12:13], 0, s[8:9]
	global_load_dwordx4 v[28:31], v[2:3], off
	s_mov_b64 s[8:9], 0x20000
	s_ashr_i32 s94, s20, 6
	v_lshl_add_u64 v[2:3], v[90:91], 0, s[8:9]
	global_load_dwordx4 v[36:39], v[2:3], off
	v_lshl_add_u64 v[2:3], v[6:7], 0, s[72:73]
	global_load_dword v128, v[2:3], off
	s_cmp_eq_u32 s94, 4
	v_and_b32_e32 v1, 63, v14
	s_cselect_b64 s[74:75], -1, 0
	s_mov_b64 s[8:9], -1
	s_and_b64 vcc, exec, s[74:75]
	v_lshlrev_b32_e32 v58, 3, v1
	s_waitcnt lgkmcnt(0)
	s_barrier
	s_cbranch_vccnz .LBB0_665
	v_and_b32_e32 v0, 64, v120
	v_lshlrev_b32_e32 v13, 3, v1
	v_add_u32_e32 v2, -1, v120
	v_add_u32_e32 v3, -2, v120
	v_add_u32_e32 v11, -4, v120
	v_add_u32_e32 v12, -8, v120
	v_add_u32_e32 v15, -16, v120
	v_subrev_u32_e32 v57, 32, v120
	s_mov_b64 s[8:9], 0

.LBB0_671:
	s_andn2_b64 vcc, exec, s[74:75]
	s_cbranch_vccnz .LBB0_675
	ds_read_b64 v[2:3], v156
	v_max_f32_e32 v4, v171, v171
	s_waitcnt lgkmcnt(0)
	v_max_f32_e32 v1, v3, v3
	s_nop 1
	v_max_f32_dpp v1, v1, v1 row_shr:1 row_mask:0xf bank_mask:0xf
	s_nop 1
	v_max_f32_dpp v1, v1, v1 row_shr:2 row_mask:0xf bank_mask:0xf
	s_nop 1
	v_max_f32_dpp v1, v1, v1 row_shr:4 row_mask:0xf bank_mask:0xf
	s_nop 1
	v_max_f32_dpp v1, v1, v1 row_shr:8 row_mask:0xf bank_mask:0xf
	s_nop 1
	v_max_f32_dpp v1, v1, v1 row_bcast:15 row_mask:0xa bank_mask:0xf
	s_nop 1
	v_max_f32_dpp v1, v1, v1 row_bcast:31 row_mask:0xc bank_mask:0xf
	s_nop 1
	v_readlane_b32 s100, v1, 63
	v_readlane_b32 s101, v2, 63
	s_nop 0
	v_mov_b32_e32 v3, s100
	v_mov_b32_e32 v0, s101
	v_max_f32_e32 v1, v1, v1
	v_max_f32_e32 v1, v4, v1
	v_add_f32_e32 v1, v2, v1
	s_waitcnt lgkmcnt(1)
	v_max_f32_e32 v3, v3, v3
	v_sub_f32_e32 v2, v2, v1
	v_max_f32_e32 v3, v4, v3
	s_waitcnt lgkmcnt(0)
	v_add_f32_e32 v172, v3, v0
	v_mul_f32_e32 v3, 0x3fb8aa3b, v2
	v_add_f32_e32 v2, v171, v2
	v_mul_f32_e32 v2, 0x3fb8aa3b, v2
	v_mul_f32_e32 v1, 0xbfb8aa3b, v1
	v_exp_f32_e32 v3, v3
	v_exp_f32_e32 v2, v2
	v_exp_f32_e32 v1, v1
	ds_write2st64_b32 v137, v3, v2 offset1:1
	ds_write_b32 v137, v1 offset:512
	s_and_saveexec_b64 s[4:5], s[10:11]
	s_cbranch_execz .LBB0_674
	v_sub_f32_e32 v1, v0, v172
	v_add_f32_e32 v0, v171, v0
	v_sub_f32_e32 v0, v0, v172
	v_mul_f32_e32 v1, 0x3fb8aa3b, v1
	v_mul_f32_e32 v0, 0x3fb8aa3b, v0
	v_exp_f32_e32 v1, v1
	v_exp_f32_e32 v0, v0
	v_mov_b32_e32 v2, s3
	ds_write_b64 v2, v[0:1]

.LBB0_699:
	s_waitcnt lgkmcnt(0)
	s_barrier
	s_and_b64 s[70:71], s[74:75], s[96:97]
	s_andn2_b64 vcc, exec, s[70:71]
	s_cbranch_vccnz .LBB0_703
	ds_read_b64 v[2:3], v156 offset:512
	v_max_f32_e32 v4, v172, v172
	s_waitcnt lgkmcnt(0)
	v_max_f32_e32 v1, v3, v3
	s_nop 1
	v_max_f32_dpp v1, v1, v1 row_shr:1 row_mask:0xf bank_mask:0xf
	s_nop 1
	v_max_f32_dpp v1, v1, v1 row_shr:2 row_mask:0xf bank_mask:0xf
	s_nop 1
	v_max_f32_dpp v1, v1, v1 row_shr:4 row_mask:0xf bank_mask:0xf
	s_nop 1
	v_max_f32_dpp v1, v1, v1 row_shr:8 row_mask:0xf bank_mask:0xf
	s_nop 1
	v_max_f32_dpp v1, v1, v1 row_bcast:15 row_mask:0xa bank_mask:0xf
	s_nop 1
	v_max_f32_dpp v1, v1, v1 row_bcast:31 row_mask:0xc bank_mask:0xf
	s_nop 1
	v_readlane_b32 s100, v1, 63
	v_readlane_b32 s101, v2, 63
	s_nop 0
	v_mov_b32_e32 v3, s100
	v_mov_b32_e32 v0, s101
	v_max_f32_e32 v1, v1, v1
	v_max_f32_e32 v1, v4, v1
	v_add_f32_e32 v1, v2, v1
	s_waitcnt lgkmcnt(1)
	v_max_f32_e32 v3, v3, v3
	v_sub_f32_e32 v2, v2, v1
	v_max_f32_e32 v3, v4, v3
	s_waitcnt lgkmcnt(0)
	v_add_f32_e32 v171, v3, v0
	v_mul_f32_e32 v3, 0x3fb8aa3b, v2
	v_add_f32_e32 v2, v172, v2
	v_mul_f32_e32 v2, 0x3fb8aa3b, v2
	v_mul_f32_e32 v1, 0xbfb8aa3b, v1
	v_exp_f32_e32 v3, v3
	v_exp_f32_e32 v2, v2
	v_exp_f32_e32 v1, v1
	ds_write2st64_b32 v153, v3, v2 offset1:1
	ds_write_b32 v153, v1 offset:512
	s_and_saveexec_b64 s[70:71], s[10:11]
	s_cbranch_execz .LBB0_702
	v_sub_f32_e32 v1, v0, v171
	v_add_f32_e32 v0, v172, v0
	v_sub_f32_e32 v0, v0, v171
	v_mul_f32_e32 v1, 0x3fb8aa3b, v1
	v_mul_f32_e32 v0, 0x3fb8aa3b, v0
	v_exp_f32_e32 v1, v1
	v_exp_f32_e32 v0, v0
	v_mov_b32_e32 v2, s78
	ds_write_b64 v2, v[0:1]
